# G1 epilogue: cross-row sums via v_permlane16/32_swap VALU exchanges instead of two ds_bpermute LDS round trips per row group
# speedup vs baseline: 1.0102x; 1.0022x over previous
.LBB0_677:
	s_ashr_i32 s42, s83, 1
	s_lshl_b32 s43, s83, 8
	s_and_b32 s59, s43, 0x100
	s_ashr_i32 s43, s42, 31
	s_lshl_b64 s[72:73], s[42:43], 9
	s_mov_b32 s43, s51
	s_lshl_b64 s[78:79], s[42:43], 23
	s_cmp_eq_u32 s42, 6
	s_cselect_b32 s43, 0, s59
	s_cselect_b32 s59, 8, 9
	s_cmp_lt_i32 s42, 2
	s_cselect_b32 s73, s73, s79
	s_cselect_b32 s72, s72, s78
	s_cselect_b32 s42, 10, s59
	s_lshl_b64 s[72:73], s[72:73], 1
	s_add_u32 s59, s76, s72
	s_addc_u32 s61, s77, s73
	s_lshl_b32 s72, s82, 10
	s_and_b32 s72, s72, 0x400
	v_add_u32_e32 v170, s72, v176
	ds_read_b32 v172, v170
	s_lshl_b32 s43, s43, 1
	s_add_u32 s43, s59, s43
	s_addc_u32 s59, s61, 0
	s_add_u32 s72, s43, s50
	s_waitcnt lgkmcnt(0)
	v_pk_mul_f32 v[136:137], v[136:137], v[172:173] op_sel_hi:[1,0]
	v_pk_mul_f32 v[134:135], v[134:135], v[172:173] op_sel_hi:[1,0]
	v_pk_mul_f32 v[188:189], v[136:137], v[136:137]
	v_pk_mul_f32 v[190:191], v[134:135], v[134:135]
	v_pk_mul_f32 v[132:133], v[132:133], v[172:173] op_sel_hi:[1,0]
	v_pk_mov_b32 v[192:193], v[190:191], v[188:189] op_sel:[1,0]
	v_mov_b32_e32 v191, v189
	v_pk_mul_f32 v[130:131], v[130:131], v[172:173] op_sel_hi:[1,0]
	v_pk_add_f32 v[188:189], v[192:193], v[190:191]
	v_pk_mul_f32 v[190:191], v[132:133], v[132:133]
	v_pk_mul_f32 v[192:193], v[130:131], v[130:131]
	v_pk_mul_f32 v[128:129], v[128:129], v[172:173] op_sel_hi:[1,0]
	v_pk_mov_b32 v[196:197], v[192:193], v[190:191] op_sel:[1,0]
	v_mov_b32_e32 v193, v191
	v_pk_add_f32 v[190:191], v[196:197], v[192:193]
	v_pk_mul_f32 v[192:193], v[126:127], v[172:173] op_sel_hi:[1,0]
	v_pk_add_f32 v[188:189], v[188:189], v[188:189] op_sel_hi:[0,1]
	v_mul_f32_e32 v126, v192, v192
	v_pk_fma_f32 v[126:127], v[192:193], v[192:193], v[126:127] op_sel_hi:[1,1,0]
	v_pk_add_f32 v[190:191], v[190:191], v[190:191] op_sel_hi:[0,1]
	v_mul_f32_e32 v126, v128, v128
	v_pk_fma_f32 v[196:197], v[128:129], v[128:129], v[126:127] op_sel_hi:[1,1,0]
	v_pk_mul_f32 v[198:199], v[124:125], v[172:173] op_sel_hi:[1,0]
	v_pk_mul_f32 v[172:173], v[122:123], v[172:173] op_sel_hi:[1,0]
	v_mul_f32_e32 v188, v198, v198
	v_mul_f32_e32 v126, v172, v172
	v_mul_f32_e32 v196, v173, v173
	v_mul_f32_e32 v190, v199, v199
	v_pk_add_f32 v[122:123], v[126:127], v[196:197]
	v_pk_add_f32 v[124:125], v[188:189], v[190:191]
	s_addc_u32 s73, s59, 0
	v_pk_add_f32 v[122:123], v[122:123], v[124:125]
	s_lshl_b32 s43, s81, 8
	v_add_f32_e32 v122, v122, v123
	v_mov_b32_e32 v123, v122
	s_nop 1
	v_permlane16_swap_b32 v122, v123
	s_nop 1
	v_add_f32_e32 v122, v122, v123
	v_add_u32_e32 v124, s43, v174
	s_and_b64 vcc, exec, s[38:39]
	s_mov_b64 s[38:39], -1
	v_mov_b32_e32 v123, v122
	s_nop 1
	v_permlane32_swap_b32 v122, v123
	s_nop 1
	v_add_f32_e32 v122, v122, v123
	v_fmamk_f32 v122, v122, 0x3c800000, v220
	v_rsq_f32_e32 v125, v122
	v_lshl_add_u64 v[122:123], v[146:147], 1, s[72:73]
	v_cndmask_b32_e64 v188, 1.0, v125, s[40:41]
	v_ashrrev_i32_e32 v125, 31, v124
	v_lshlrev_b64 v[124:125], s42, v[124:125]
	v_lshl_add_u64 v[190:191], v[124:125], 1, v[122:123]
	v_pk_mul_f32 v[124:125], v[134:135], v[188:189] op_sel_hi:[1,0]
	v_pk_mul_f32 v[126:127], v[136:137], v[188:189] op_sel_hi:[1,0]
	v_pk_mul_f32 v[124:125], v[156:157], v[124:125]
	v_pk_mul_f32 v[126:127], v[158:159], v[126:127]
	v_pk_mul_f32 v[130:131], v[130:131], v[188:189] op_sel_hi:[1,0]
	v_pk_mul_f32 v[132:133], v[132:133], v[188:189] op_sel_hi:[1,0]
	v_pk_mul_f32 v[130:131], v[154:155], v[130:131]
	v_pk_mul_f32 v[132:133], v[160:161], v[132:133]
	v_cvt_pk_bf16_f32 v124, v124, v125
	v_cvt_pk_bf16_f32 v125, v126, v127
	v_cvt_pk_bf16_f32 v126, v130, v131
	v_pk_mul_f32 v[130:131], v[198:199], v[188:189] op_sel_hi:[1,0]
	v_cvt_pk_bf16_f32 v127, v132, v133
	global_store_dwordx4 v[190:191], v[124:127], off
	v_pk_mul_f32 v[130:131], v[168:169], v[130:131]
	s_nop 0
	v_pk_mul_f32 v[124:125], v[192:193], v[188:189] op_sel_hi:[1,0]
	v_pk_mul_f32 v[126:127], v[128:129], v[188:189] op_sel_hi:[1,0]
	v_pk_mul_f32 v[124:125], v[164:165], v[124:125]
	v_pk_mul_f32 v[126:127], v[166:167], v[126:127]
	v_pk_mul_f32 v[128:129], v[172:173], v[188:189] op_sel_hi:[1,0]
	v_cvt_pk_bf16_f32 v124, v124, v125
	v_cvt_pk_bf16_f32 v125, v126, v127
	s_nop 0
	v_pk_mul_f32 v[128:129], v[162:163], v[128:129]
	s_nop 0
	v_cvt_pk_bf16_f32 v126, v128, v129
	v_cvt_pk_bf16_f32 v127, v130, v131
	global_store_dwordx4 v[190:191], v[124:127], off offset:64
	ds_read_b32 v124, v170 offset:64
	s_waitcnt lgkmcnt(0)
	v_pk_mul_f32 v[120:121], v[120:121], v[124:125] op_sel_hi:[1,0]
	v_pk_mul_f32 v[118:119], v[118:119], v[124:125] op_sel_hi:[1,0]
	v_pk_mul_f32 v[126:127], v[120:121], v[120:121]
	v_pk_mul_f32 v[128:129], v[118:119], v[118:119]
	v_pk_mul_f32 v[116:117], v[116:117], v[124:125] op_sel_hi:[1,0]
	v_pk_mov_b32 v[130:131], v[128:129], v[126:127] op_sel:[1,0]
	v_mov_b32_e32 v129, v127
	v_pk_add_f32 v[126:127], v[130:131], v[128:129]
	v_pk_mul_f32 v[114:115], v[114:115], v[124:125] op_sel_hi:[1,0]
	v_pk_add_f32 v[126:127], v[126:127], v[126:127] op_sel_hi:[0,1]
	v_pk_mul_f32 v[128:129], v[116:117], v[116:117]
	v_pk_mul_f32 v[130:131], v[114:115], v[114:115]
	v_pk_mul_f32 v[110:111], v[110:111], v[124:125] op_sel_hi:[1,0]
	v_pk_mov_b32 v[132:133], v[130:131], v[128:129] op_sel:[1,0]
	v_mov_b32_e32 v131, v129
	v_pk_mul_f32 v[112:113], v[112:113], v[124:125] op_sel_hi:[1,0]
	v_mul_f32_e32 v126, v110, v110
	v_pk_add_f32 v[128:129], v[132:133], v[130:131]
	v_pk_fma_f32 v[130:131], v[110:111], v[110:111], v[126:127] op_sel_hi:[1,1,0]
	v_mul_f32_e32 v126, v112, v112
	v_pk_add_f32 v[128:129], v[128:129], v[128:129] op_sel_hi:[0,1]
	v_pk_fma_f32 v[132:133], v[112:113], v[112:113], v[126:127] op_sel_hi:[1,1,0]
	v_pk_mul_f32 v[134:135], v[108:109], v[124:125] op_sel_hi:[1,0]
	v_pk_mul_f32 v[124:125], v[106:107], v[124:125] op_sel_hi:[1,0]
	v_mul_f32_e32 v126, v134, v134
	v_mul_f32_e32 v130, v124, v124
	v_mul_f32_e32 v132, v125, v125
	v_mul_f32_e32 v128, v135, v135
	v_pk_add_f32 v[106:107], v[130:131], v[132:133]
	v_pk_add_f32 v[108:109], v[126:127], v[128:129]
	s_nop 0
	v_pk_add_f32 v[106:107], v[106:107], v[108:109]
	s_nop 0
	v_add_f32_e32 v106, v106, v107
	v_mov_b32_e32 v107, v106
	s_nop 1
	v_permlane16_swap_b32 v106, v107
	s_nop 1
	v_add_f32_e32 v106, v106, v107
	v_mov_b32_e32 v107, v106
	s_nop 1
	v_permlane32_swap_b32 v106, v107
	s_nop 1
	v_add_f32_e32 v106, v106, v107
	v_fmamk_f32 v106, v106, 0x3c800000, v220
	v_rsq_f32_e32 v107, v106
	v_add_u32_e32 v106, s43, v180
	v_cndmask_b32_e64 v126, 1.0, v107, s[40:41]
	v_ashrrev_i32_e32 v107, 31, v106
	v_lshlrev_b64 v[106:107], s42, v[106:107]
	v_lshl_add_u64 v[128:129], v[106:107], 1, v[122:123]
	v_pk_mul_f32 v[106:107], v[118:119], v[126:127] op_sel_hi:[1,0]
	v_pk_mul_f32 v[108:109], v[120:121], v[126:127] op_sel_hi:[1,0]
	v_pk_mul_f32 v[106:107], v[156:157], v[106:107]
	v_pk_mul_f32 v[108:109], v[158:159], v[108:109]
	v_pk_mul_f32 v[114:115], v[114:115], v[126:127] op_sel_hi:[1,0]
	v_pk_mul_f32 v[116:117], v[116:117], v[126:127] op_sel_hi:[1,0]
	v_pk_mul_f32 v[114:115], v[154:155], v[114:115]
	v_pk_mul_f32 v[116:117], v[160:161], v[116:117]
	v_cvt_pk_bf16_f32 v106, v106, v107
	v_cvt_pk_bf16_f32 v107, v108, v109
	v_cvt_pk_bf16_f32 v108, v114, v115
	s_nop 0
	v_cvt_pk_bf16_f32 v109, v116, v117
	global_store_dwordx4 v[128:129], v[106:109], off
	s_nop 1
	v_pk_mul_f32 v[106:107], v[110:111], v[126:127] op_sel_hi:[1,0]
	v_pk_mul_f32 v[108:109], v[112:113], v[126:127] op_sel_hi:[1,0]
	v_pk_mul_f32 v[106:107], v[164:165], v[106:107]
	v_pk_mul_f32 v[108:109], v[166:167], v[108:109]
	v_pk_mul_f32 v[110:111], v[124:125], v[126:127] op_sel_hi:[1,0]
	v_pk_mul_f32 v[112:113], v[134:135], v[126:127] op_sel_hi:[1,0]
	v_pk_mul_f32 v[110:111], v[162:163], v[110:111]
	v_pk_mul_f32 v[112:113], v[168:169], v[112:113]
	v_cvt_pk_bf16_f32 v106, v106, v107
	v_cvt_pk_bf16_f32 v107, v108, v109
	v_cvt_pk_bf16_f32 v108, v110, v111
	s_nop 0
	v_cvt_pk_bf16_f32 v109, v112, v113
	global_store_dwordx4 v[128:129], v[106:109], off offset:64
	ds_read_b32 v106, v170 offset:128
	s_waitcnt lgkmcnt(0)
	v_pk_mul_f32 v[104:105], v[104:105], v[106:107] op_sel_hi:[1,0]
	v_pk_mul_f32 v[102:103], v[102:103], v[106:107] op_sel_hi:[1,0]
	v_pk_mul_f32 v[108:109], v[104:105], v[104:105]
	v_pk_mul_f32 v[110:111], v[102:103], v[102:103]
	v_pk_mul_f32 v[100:101], v[100:101], v[106:107] op_sel_hi:[1,0]
	v_pk_mov_b32 v[112:113], v[110:111], v[108:109] op_sel:[1,0]
	v_mov_b32_e32 v111, v109
	v_pk_add_f32 v[108:109], v[112:113], v[110:111]
	v_pk_mul_f32 v[98:99], v[98:99], v[106:107] op_sel_hi:[1,0]
	v_pk_add_f32 v[108:109], v[108:109], v[108:109] op_sel_hi:[0,1]
	v_pk_mul_f32 v[110:111], v[100:101], v[100:101]
	v_pk_mul_f32 v[112:113], v[98:99], v[98:99]
	v_pk_mul_f32 v[94:95], v[94:95], v[106:107] op_sel_hi:[1,0]
	v_pk_mov_b32 v[114:115], v[112:113], v[110:111] op_sel:[1,0]
	v_mov_b32_e32 v113, v111
	v_pk_mul_f32 v[96:97], v[96:97], v[106:107] op_sel_hi:[1,0]
	v_mul_f32_e32 v108, v94, v94
	v_pk_add_f32 v[110:111], v[114:115], v[112:113]
	v_pk_fma_f32 v[112:113], v[94:95], v[94:95], v[108:109] op_sel_hi:[1,1,0]
	v_mul_f32_e32 v108, v96, v96
	v_pk_add_f32 v[110:111], v[110:111], v[110:111] op_sel_hi:[0,1]
	v_pk_fma_f32 v[114:115], v[96:97], v[96:97], v[108:109] op_sel_hi:[1,1,0]
	v_pk_mul_f32 v[116:117], v[92:93], v[106:107] op_sel_hi:[1,0]
	v_pk_mul_f32 v[106:107], v[90:91], v[106:107] op_sel_hi:[1,0]
	v_mul_f32_e32 v108, v116, v116
	v_mul_f32_e32 v112, v106, v106
	v_mul_f32_e32 v114, v107, v107
	v_mul_f32_e32 v110, v117, v117
	v_pk_add_f32 v[90:91], v[112:113], v[114:115]
	v_pk_add_f32 v[92:93], v[108:109], v[110:111]
	s_nop 0
	v_pk_add_f32 v[90:91], v[90:91], v[92:93]
	s_nop 0
	v_add_f32_e32 v90, v90, v91
	v_mov_b32_e32 v91, v90
	s_nop 1
	v_permlane16_swap_b32 v90, v91
	s_nop 1
	v_add_f32_e32 v90, v90, v91
	v_mov_b32_e32 v91, v90
	s_nop 1
	v_permlane32_swap_b32 v90, v91
	s_nop 1
	v_add_f32_e32 v90, v90, v91
	v_fmamk_f32 v90, v90, 0x3c800000, v220
	v_rsq_f32_e32 v91, v90
	v_add_u32_e32 v90, s43, v181
	v_cndmask_b32_e64 v108, 1.0, v91, s[40:41]
	v_ashrrev_i32_e32 v91, 31, v90
	v_lshlrev_b64 v[90:91], s42, v[90:91]
	v_lshl_add_u64 v[110:111], v[90:91], 1, v[122:123]
	v_pk_mul_f32 v[90:91], v[102:103], v[108:109] op_sel_hi:[1,0]
	v_pk_mul_f32 v[92:93], v[104:105], v[108:109] op_sel_hi:[1,0]
	v_pk_mul_f32 v[90:91], v[156:157], v[90:91]
	v_pk_mul_f32 v[92:93], v[158:159], v[92:93]
	v_pk_mul_f32 v[98:99], v[98:99], v[108:109] op_sel_hi:[1,0]
	v_pk_mul_f32 v[100:101], v[100:101], v[108:109] op_sel_hi:[1,0]
	v_pk_mul_f32 v[98:99], v[154:155], v[98:99]
	v_pk_mul_f32 v[100:101], v[160:161], v[100:101]
	v_cvt_pk_bf16_f32 v90, v90, v91
	v_cvt_pk_bf16_f32 v91, v92, v93
	v_cvt_pk_bf16_f32 v92, v98, v99
	s_nop 0
	v_cvt_pk_bf16_f32 v93, v100, v101
	global_store_dwordx4 v[110:111], v[90:93], off
	s_nop 1
	v_pk_mul_f32 v[90:91], v[94:95], v[108:109] op_sel_hi:[1,0]
	v_pk_mul_f32 v[92:93], v[96:97], v[108:109] op_sel_hi:[1,0]
	v_pk_mul_f32 v[90:91], v[164:165], v[90:91]
	v_pk_mul_f32 v[92:93], v[166:167], v[92:93]
	v_pk_mul_f32 v[94:95], v[106:107], v[108:109] op_sel_hi:[1,0]
	v_pk_mul_f32 v[96:97], v[116:117], v[108:109] op_sel_hi:[1,0]
	v_pk_mul_f32 v[94:95], v[162:163], v[94:95]
	v_pk_mul_f32 v[96:97], v[168:169], v[96:97]
	v_cvt_pk_bf16_f32 v90, v90, v91
	v_cvt_pk_bf16_f32 v91, v92, v93
	v_cvt_pk_bf16_f32 v92, v94, v95
	s_nop 0
	v_cvt_pk_bf16_f32 v93, v96, v97
	global_store_dwordx4 v[110:111], v[90:93], off offset:64
	ds_read_b32 v90, v170 offset:192
	s_waitcnt lgkmcnt(0)
	v_pk_mul_f32 v[88:89], v[88:89], v[90:91] op_sel_hi:[1,0]
	v_pk_mul_f32 v[86:87], v[86:87], v[90:91] op_sel_hi:[1,0]
	v_pk_mul_f32 v[92:93], v[88:89], v[88:89]
	v_pk_mul_f32 v[94:95], v[86:87], v[86:87]
	v_pk_mul_f32 v[84:85], v[84:85], v[90:91] op_sel_hi:[1,0]
	v_pk_mov_b32 v[96:97], v[94:95], v[92:93] op_sel:[1,0]
	v_mov_b32_e32 v95, v93
	v_pk_add_f32 v[92:93], v[96:97], v[94:95]
	v_pk_mul_f32 v[82:83], v[82:83], v[90:91] op_sel_hi:[1,0]
	v_pk_add_f32 v[92:93], v[92:93], v[92:93] op_sel_hi:[0,1]
	v_pk_mul_f32 v[94:95], v[84:85], v[84:85]
	v_pk_mul_f32 v[96:97], v[82:83], v[82:83]
	v_pk_mul_f32 v[78:79], v[78:79], v[90:91] op_sel_hi:[1,0]
	v_pk_mov_b32 v[98:99], v[96:97], v[94:95] op_sel:[1,0]
	v_mov_b32_e32 v97, v95
	v_pk_mul_f32 v[80:81], v[80:81], v[90:91] op_sel_hi:[1,0]
	v_mul_f32_e32 v92, v78, v78
	v_pk_add_f32 v[94:95], v[98:99], v[96:97]
	v_pk_fma_f32 v[96:97], v[78:79], v[78:79], v[92:93] op_sel_hi:[1,1,0]
	v_mul_f32_e32 v92, v80, v80
	v_pk_add_f32 v[94:95], v[94:95], v[94:95] op_sel_hi:[0,1]
	v_pk_fma_f32 v[98:99], v[80:81], v[80:81], v[92:93] op_sel_hi:[1,1,0]
	v_pk_mul_f32 v[100:101], v[76:77], v[90:91] op_sel_hi:[1,0]
	v_pk_mul_f32 v[90:91], v[74:75], v[90:91] op_sel_hi:[1,0]
	v_mul_f32_e32 v92, v100, v100
	v_mul_f32_e32 v96, v90, v90
	v_mul_f32_e32 v98, v91, v91
	v_mul_f32_e32 v94, v101, v101
	v_pk_add_f32 v[74:75], v[96:97], v[98:99]
	v_pk_add_f32 v[76:77], v[92:93], v[94:95]
	s_nop 0
	v_pk_add_f32 v[74:75], v[74:75], v[76:77]
	s_nop 0
	v_add_f32_e32 v74, v74, v75
	v_mov_b32_e32 v75, v74
	s_nop 1
	v_permlane16_swap_b32 v74, v75
	s_nop 1
	v_add_f32_e32 v74, v74, v75
	v_mov_b32_e32 v75, v74
	s_nop 1
	v_permlane32_swap_b32 v74, v75
	s_nop 1
	v_add_f32_e32 v74, v74, v75
	v_fmamk_f32 v74, v74, 0x3c800000, v220
	v_rsq_f32_e32 v75, v74
	v_add_u32_e32 v74, s43, v182
	v_cndmask_b32_e64 v92, 1.0, v75, s[40:41]
	v_ashrrev_i32_e32 v75, 31, v74
	v_lshlrev_b64 v[74:75], s42, v[74:75]
	v_lshl_add_u64 v[94:95], v[74:75], 1, v[122:123]
	v_pk_mul_f32 v[74:75], v[86:87], v[92:93] op_sel_hi:[1,0]
	v_pk_mul_f32 v[76:77], v[88:89], v[92:93] op_sel_hi:[1,0]
	v_pk_mul_f32 v[74:75], v[156:157], v[74:75]
	v_pk_mul_f32 v[76:77], v[158:159], v[76:77]
	v_pk_mul_f32 v[82:83], v[82:83], v[92:93] op_sel_hi:[1,0]
	v_pk_mul_f32 v[84:85], v[84:85], v[92:93] op_sel_hi:[1,0]
	v_pk_mul_f32 v[82:83], v[154:155], v[82:83]
	v_pk_mul_f32 v[84:85], v[160:161], v[84:85]
	v_cvt_pk_bf16_f32 v74, v74, v75
	v_cvt_pk_bf16_f32 v75, v76, v77
	v_cvt_pk_bf16_f32 v76, v82, v83
	s_nop 0
	v_cvt_pk_bf16_f32 v77, v84, v85
	global_store_dwordx4 v[94:95], v[74:77], off
	s_nop 1
	v_pk_mul_f32 v[74:75], v[78:79], v[92:93] op_sel_hi:[1,0]
	v_pk_mul_f32 v[76:77], v[80:81], v[92:93] op_sel_hi:[1,0]
	v_pk_mul_f32 v[74:75], v[164:165], v[74:75]
	v_pk_mul_f32 v[76:77], v[166:167], v[76:77]
	v_pk_mul_f32 v[78:79], v[90:91], v[92:93] op_sel_hi:[1,0]
	v_pk_mul_f32 v[80:81], v[100:101], v[92:93] op_sel_hi:[1,0]
	v_pk_mul_f32 v[78:79], v[162:163], v[78:79]
	v_pk_mul_f32 v[80:81], v[168:169], v[80:81]
	v_cvt_pk_bf16_f32 v74, v74, v75
	v_cvt_pk_bf16_f32 v75, v76, v77
	v_cvt_pk_bf16_f32 v76, v78, v79
	s_nop 0
	v_cvt_pk_bf16_f32 v77, v80, v81
	global_store_dwordx4 v[94:95], v[74:77], off offset:64
	ds_read_b32 v74, v170 offset:512
	s_waitcnt lgkmcnt(0)
	v_pk_mul_f32 v[72:73], v[72:73], v[74:75] op_sel_hi:[1,0]
	v_pk_mul_f32 v[70:71], v[70:71], v[74:75] op_sel_hi:[1,0]
	v_pk_mul_f32 v[76:77], v[72:73], v[72:73]
	v_pk_mul_f32 v[78:79], v[70:71], v[70:71]
	v_pk_mul_f32 v[68:69], v[68:69], v[74:75] op_sel_hi:[1,0]
	v_pk_mov_b32 v[80:81], v[78:79], v[76:77] op_sel:[1,0]
	v_mov_b32_e32 v79, v77
	v_pk_add_f32 v[76:77], v[80:81], v[78:79]
	v_pk_mul_f32 v[66:67], v[66:67], v[74:75] op_sel_hi:[1,0]
	v_pk_add_f32 v[76:77], v[76:77], v[76:77] op_sel_hi:[0,1]
	v_pk_mul_f32 v[78:79], v[68:69], v[68:69]
	v_pk_mul_f32 v[80:81], v[66:67], v[66:67]
	v_pk_mul_f32 v[62:63], v[62:63], v[74:75] op_sel_hi:[1,0]
	v_pk_mov_b32 v[82:83], v[80:81], v[78:79] op_sel:[1,0]
	v_mov_b32_e32 v81, v79
	v_pk_mul_f32 v[64:65], v[64:65], v[74:75] op_sel_hi:[1,0]
	v_mul_f32_e32 v76, v62, v62
	v_pk_add_f32 v[78:79], v[82:83], v[80:81]
	v_pk_fma_f32 v[80:81], v[62:63], v[62:63], v[76:77] op_sel_hi:[1,1,0]
	v_mul_f32_e32 v76, v64, v64
	v_pk_add_f32 v[78:79], v[78:79], v[78:79] op_sel_hi:[0,1]
	v_pk_fma_f32 v[82:83], v[64:65], v[64:65], v[76:77] op_sel_hi:[1,1,0]
	v_pk_mul_f32 v[84:85], v[60:61], v[74:75] op_sel_hi:[1,0]
	v_pk_mul_f32 v[74:75], v[58:59], v[74:75] op_sel_hi:[1,0]
	v_mul_f32_e32 v76, v84, v84
	v_mul_f32_e32 v80, v74, v74
	v_mul_f32_e32 v82, v75, v75
	v_mul_f32_e32 v78, v85, v85
	v_pk_add_f32 v[58:59], v[80:81], v[82:83]
	v_pk_add_f32 v[60:61], v[76:77], v[78:79]
	s_nop 0
	v_pk_add_f32 v[58:59], v[58:59], v[60:61]
	s_nop 0
	v_add_f32_e32 v58, v58, v59
	v_mov_b32_e32 v59, v58
	s_nop 1
	v_permlane16_swap_b32 v58, v59
	s_nop 1
	v_add_f32_e32 v58, v58, v59
	v_mov_b32_e32 v59, v58
	s_nop 1
	v_permlane32_swap_b32 v58, v59
	s_nop 1
	v_add_f32_e32 v58, v58, v59
	v_fmamk_f32 v58, v58, 0x3c800000, v220
	v_rsq_f32_e32 v59, v58
	v_add_u32_e32 v58, s43, v183
	v_cndmask_b32_e64 v76, 1.0, v59, s[40:41]
	v_ashrrev_i32_e32 v59, 31, v58
	v_lshlrev_b64 v[58:59], s42, v[58:59]
	v_lshl_add_u64 v[78:79], v[58:59], 1, v[122:123]
	v_pk_mul_f32 v[58:59], v[70:71], v[76:77] op_sel_hi:[1,0]
	v_pk_mul_f32 v[60:61], v[72:73], v[76:77] op_sel_hi:[1,0]
	v_pk_mul_f32 v[58:59], v[156:157], v[58:59]
	v_pk_mul_f32 v[60:61], v[158:159], v[60:61]
	v_pk_mul_f32 v[66:67], v[66:67], v[76:77] op_sel_hi:[1,0]
	v_pk_mul_f32 v[68:69], v[68:69], v[76:77] op_sel_hi:[1,0]
	v_pk_mul_f32 v[66:67], v[154:155], v[66:67]
	v_pk_mul_f32 v[68:69], v[160:161], v[68:69]
	v_cvt_pk_bf16_f32 v58, v58, v59
	v_cvt_pk_bf16_f32 v59, v60, v61
	v_cvt_pk_bf16_f32 v60, v66, v67
	s_nop 0
	v_cvt_pk_bf16_f32 v61, v68, v69
	global_store_dwordx4 v[78:79], v[58:61], off
	s_nop 1
	v_pk_mul_f32 v[58:59], v[62:63], v[76:77] op_sel_hi:[1,0]
	v_pk_mul_f32 v[60:61], v[64:65], v[76:77] op_sel_hi:[1,0]
	v_pk_mul_f32 v[58:59], v[164:165], v[58:59]
	v_pk_mul_f32 v[60:61], v[166:167], v[60:61]
	v_pk_mul_f32 v[62:63], v[74:75], v[76:77] op_sel_hi:[1,0]
	v_pk_mul_f32 v[64:65], v[84:85], v[76:77] op_sel_hi:[1,0]
	v_pk_mul_f32 v[62:63], v[162:163], v[62:63]
	v_pk_mul_f32 v[64:65], v[168:169], v[64:65]
	v_cvt_pk_bf16_f32 v58, v58, v59
	v_cvt_pk_bf16_f32 v59, v60, v61
	v_cvt_pk_bf16_f32 v60, v62, v63
	s_nop 0
	v_cvt_pk_bf16_f32 v61, v64, v65
	global_store_dwordx4 v[78:79], v[58:61], off offset:64
	ds_read_b32 v58, v170 offset:576
	s_waitcnt lgkmcnt(0)
	v_pk_mul_f32 v[56:57], v[56:57], v[58:59] op_sel_hi:[1,0]
	v_pk_mul_f32 v[54:55], v[54:55], v[58:59] op_sel_hi:[1,0]
	v_pk_mul_f32 v[60:61], v[56:57], v[56:57]
	v_pk_mul_f32 v[62:63], v[54:55], v[54:55]
	v_pk_mul_f32 v[52:53], v[52:53], v[58:59] op_sel_hi:[1,0]
	v_pk_mov_b32 v[64:65], v[62:63], v[60:61] op_sel:[1,0]
	v_mov_b32_e32 v63, v61
	v_pk_add_f32 v[60:61], v[64:65], v[62:63]
	v_pk_mul_f32 v[50:51], v[50:51], v[58:59] op_sel_hi:[1,0]
	v_pk_add_f32 v[60:61], v[60:61], v[60:61] op_sel_hi:[0,1]
	v_pk_mul_f32 v[62:63], v[52:53], v[52:53]
	v_pk_mul_f32 v[64:65], v[50:51], v[50:51]
	v_pk_mul_f32 v[46:47], v[46:47], v[58:59] op_sel_hi:[1,0]
	v_pk_mov_b32 v[66:67], v[64:65], v[62:63] op_sel:[1,0]
	v_mov_b32_e32 v65, v63
	v_pk_mul_f32 v[48:49], v[48:49], v[58:59] op_sel_hi:[1,0]
	v_mul_f32_e32 v60, v46, v46
	v_pk_add_f32 v[62:63], v[66:67], v[64:65]
	v_pk_fma_f32 v[64:65], v[46:47], v[46:47], v[60:61] op_sel_hi:[1,1,0]
	v_mul_f32_e32 v60, v48, v48
	v_pk_add_f32 v[62:63], v[62:63], v[62:63] op_sel_hi:[0,1]
	v_pk_fma_f32 v[66:67], v[48:49], v[48:49], v[60:61] op_sel_hi:[1,1,0]
	v_pk_mul_f32 v[68:69], v[44:45], v[58:59] op_sel_hi:[1,0]
	v_pk_mul_f32 v[58:59], v[42:43], v[58:59] op_sel_hi:[1,0]
	v_mul_f32_e32 v60, v68, v68
	v_mul_f32_e32 v64, v58, v58
	v_mul_f32_e32 v66, v59, v59
	v_mul_f32_e32 v62, v69, v69
	v_pk_add_f32 v[42:43], v[64:65], v[66:67]
	v_pk_add_f32 v[44:45], v[60:61], v[62:63]
	s_nop 0
	v_pk_add_f32 v[42:43], v[42:43], v[44:45]
	s_nop 0
	v_add_f32_e32 v42, v42, v43
	v_mov_b32_e32 v43, v42
	s_nop 1
	v_permlane16_swap_b32 v42, v43
	s_nop 1
	v_add_f32_e32 v42, v42, v43
	v_mov_b32_e32 v43, v42
	s_nop 1
	v_permlane32_swap_b32 v42, v43
	s_nop 1
	v_add_f32_e32 v42, v42, v43
	v_fmamk_f32 v42, v42, 0x3c800000, v220
	v_rsq_f32_e32 v43, v42
	v_add_u32_e32 v42, s43, v184
	v_cndmask_b32_e64 v60, 1.0, v43, s[40:41]
	v_ashrrev_i32_e32 v43, 31, v42
	v_lshlrev_b64 v[42:43], s42, v[42:43]
	v_lshl_add_u64 v[62:63], v[42:43], 1, v[122:123]
	v_pk_mul_f32 v[42:43], v[54:55], v[60:61] op_sel_hi:[1,0]
	v_pk_mul_f32 v[44:45], v[56:57], v[60:61] op_sel_hi:[1,0]
	v_pk_mul_f32 v[42:43], v[156:157], v[42:43]
	v_pk_mul_f32 v[44:45], v[158:159], v[44:45]
	v_pk_mul_f32 v[50:51], v[50:51], v[60:61] op_sel_hi:[1,0]
	v_pk_mul_f32 v[52:53], v[52:53], v[60:61] op_sel_hi:[1,0]
	v_pk_mul_f32 v[50:51], v[154:155], v[50:51]
	v_pk_mul_f32 v[52:53], v[160:161], v[52:53]
	v_cvt_pk_bf16_f32 v42, v42, v43
	v_cvt_pk_bf16_f32 v43, v44, v45
	v_cvt_pk_bf16_f32 v44, v50, v51
	s_nop 0
	v_cvt_pk_bf16_f32 v45, v52, v53
	global_store_dwordx4 v[62:63], v[42:45], off
	s_nop 1
	v_pk_mul_f32 v[42:43], v[46:47], v[60:61] op_sel_hi:[1,0]
	v_pk_mul_f32 v[44:45], v[48:49], v[60:61] op_sel_hi:[1,0]
	v_pk_mul_f32 v[42:43], v[164:165], v[42:43]
	v_pk_mul_f32 v[44:45], v[166:167], v[44:45]
	v_pk_mul_f32 v[46:47], v[58:59], v[60:61] op_sel_hi:[1,0]
	v_pk_mul_f32 v[48:49], v[68:69], v[60:61] op_sel_hi:[1,0]
	v_pk_mul_f32 v[46:47], v[162:163], v[46:47]
	v_pk_mul_f32 v[48:49], v[168:169], v[48:49]
	v_cvt_pk_bf16_f32 v42, v42, v43
	v_cvt_pk_bf16_f32 v43, v44, v45
	v_cvt_pk_bf16_f32 v44, v46, v47
	s_nop 0
	v_cvt_pk_bf16_f32 v45, v48, v49
	global_store_dwordx4 v[62:63], v[42:45], off offset:64
	ds_read_b32 v42, v170 offset:640
	s_waitcnt lgkmcnt(0)
	v_pk_mul_f32 v[40:41], v[40:41], v[42:43] op_sel_hi:[1,0]
	v_pk_mul_f32 v[38:39], v[38:39], v[42:43] op_sel_hi:[1,0]
	v_pk_mul_f32 v[44:45], v[40:41], v[40:41]
	v_pk_mul_f32 v[46:47], v[38:39], v[38:39]
	v_pk_mul_f32 v[36:37], v[36:37], v[42:43] op_sel_hi:[1,0]
	v_pk_mov_b32 v[48:49], v[46:47], v[44:45] op_sel:[1,0]
	v_mov_b32_e32 v47, v45
	v_pk_add_f32 v[44:45], v[48:49], v[46:47]
	v_pk_mul_f32 v[34:35], v[34:35], v[42:43] op_sel_hi:[1,0]
	v_pk_add_f32 v[44:45], v[44:45], v[44:45] op_sel_hi:[0,1]
	v_pk_mul_f32 v[46:47], v[36:37], v[36:37]
	v_pk_mul_f32 v[48:49], v[34:35], v[34:35]
	v_pk_mul_f32 v[30:31], v[30:31], v[42:43] op_sel_hi:[1,0]
	v_pk_mov_b32 v[50:51], v[48:49], v[46:47] op_sel:[1,0]
	v_mov_b32_e32 v49, v47
	v_pk_mul_f32 v[32:33], v[32:33], v[42:43] op_sel_hi:[1,0]
	v_mul_f32_e32 v44, v30, v30
	v_pk_add_f32 v[46:47], v[50:51], v[48:49]
	v_pk_fma_f32 v[48:49], v[30:31], v[30:31], v[44:45] op_sel_hi:[1,1,0]
	v_mul_f32_e32 v44, v32, v32
	v_pk_add_f32 v[46:47], v[46:47], v[46:47] op_sel_hi:[0,1]
	v_pk_fma_f32 v[50:51], v[32:33], v[32:33], v[44:45] op_sel_hi:[1,1,0]
	v_pk_mul_f32 v[52:53], v[28:29], v[42:43] op_sel_hi:[1,0]
	v_pk_mul_f32 v[42:43], v[26:27], v[42:43] op_sel_hi:[1,0]
	v_mul_f32_e32 v44, v52, v52
	v_mul_f32_e32 v48, v42, v42
	v_mul_f32_e32 v50, v43, v43
	v_mul_f32_e32 v46, v53, v53
	v_pk_add_f32 v[26:27], v[48:49], v[50:51]
	v_pk_add_f32 v[28:29], v[44:45], v[46:47]
	s_nop 0
	v_pk_add_f32 v[26:27], v[26:27], v[28:29]
	s_nop 0
	v_add_f32_e32 v26, v26, v27
	v_mov_b32_e32 v27, v26
	s_nop 1
	v_permlane16_swap_b32 v26, v27
	s_nop 1
	v_add_f32_e32 v26, v26, v27
	v_mov_b32_e32 v27, v26
	s_nop 1
	v_permlane32_swap_b32 v26, v27
	s_nop 1
	v_add_f32_e32 v26, v26, v27
	v_fmamk_f32 v26, v26, 0x3c800000, v220
	v_rsq_f32_e32 v27, v26
	v_add_u32_e32 v26, s43, v185
	v_cndmask_b32_e64 v44, 1.0, v27, s[40:41]
	v_ashrrev_i32_e32 v27, 31, v26
	v_lshlrev_b64 v[26:27], s42, v[26:27]
	v_lshl_add_u64 v[46:47], v[26:27], 1, v[122:123]
	v_pk_mul_f32 v[26:27], v[38:39], v[44:45] op_sel_hi:[1,0]
	v_pk_mul_f32 v[28:29], v[40:41], v[44:45] op_sel_hi:[1,0]
	v_pk_mul_f32 v[26:27], v[156:157], v[26:27]
	v_pk_mul_f32 v[28:29], v[158:159], v[28:29]
	v_pk_mul_f32 v[34:35], v[34:35], v[44:45] op_sel_hi:[1,0]
	v_pk_mul_f32 v[36:37], v[36:37], v[44:45] op_sel_hi:[1,0]
	v_pk_mul_f32 v[34:35], v[154:155], v[34:35]
	v_pk_mul_f32 v[36:37], v[160:161], v[36:37]
	v_cvt_pk_bf16_f32 v26, v26, v27
	v_cvt_pk_bf16_f32 v27, v28, v29
	v_cvt_pk_bf16_f32 v28, v34, v35
	s_nop 0
	v_cvt_pk_bf16_f32 v29, v36, v37
	global_store_dwordx4 v[46:47], v[26:29], off
	s_nop 1
	v_pk_mul_f32 v[26:27], v[30:31], v[44:45] op_sel_hi:[1,0]
	v_pk_mul_f32 v[28:29], v[32:33], v[44:45] op_sel_hi:[1,0]
	v_pk_mul_f32 v[26:27], v[164:165], v[26:27]
	v_pk_mul_f32 v[28:29], v[166:167], v[28:29]
	v_pk_mul_f32 v[30:31], v[42:43], v[44:45] op_sel_hi:[1,0]
	v_pk_mul_f32 v[32:33], v[52:53], v[44:45] op_sel_hi:[1,0]
	v_pk_mul_f32 v[30:31], v[162:163], v[30:31]
	v_pk_mul_f32 v[32:33], v[168:169], v[32:33]
	v_cvt_pk_bf16_f32 v26, v26, v27
	v_cvt_pk_bf16_f32 v27, v28, v29
	v_cvt_pk_bf16_f32 v28, v30, v31
	s_nop 0
	v_cvt_pk_bf16_f32 v29, v32, v33
	global_store_dwordx4 v[46:47], v[26:29], off offset:64
	ds_read_b32 v26, v170 offset:704
	s_waitcnt lgkmcnt(0)
	v_pk_mul_f32 v[24:25], v[24:25], v[26:27] op_sel_hi:[1,0]
	v_pk_mul_f32 v[22:23], v[22:23], v[26:27] op_sel_hi:[1,0]
	v_pk_mul_f32 v[28:29], v[24:25], v[24:25]
	v_pk_mul_f32 v[30:31], v[22:23], v[22:23]
	v_pk_mul_f32 v[20:21], v[20:21], v[26:27] op_sel_hi:[1,0]
	v_pk_mov_b32 v[32:33], v[30:31], v[28:29] op_sel:[1,0]
	v_mov_b32_e32 v31, v29
	v_pk_add_f32 v[28:29], v[32:33], v[30:31]
	v_pk_mul_f32 v[18:19], v[18:19], v[26:27] op_sel_hi:[1,0]
	v_pk_add_f32 v[28:29], v[28:29], v[28:29] op_sel_hi:[0,1]
	v_pk_mul_f32 v[30:31], v[20:21], v[20:21]
	v_pk_mul_f32 v[32:33], v[18:19], v[18:19]
	v_pk_mul_f32 v[14:15], v[14:15], v[26:27] op_sel_hi:[1,0]
	v_pk_mov_b32 v[34:35], v[32:33], v[30:31] op_sel:[1,0]
	v_mov_b32_e32 v33, v31
	v_pk_mul_f32 v[16:17], v[16:17], v[26:27] op_sel_hi:[1,0]
	v_mul_f32_e32 v28, v14, v14
	v_pk_add_f32 v[30:31], v[34:35], v[32:33]
	v_pk_fma_f32 v[32:33], v[14:15], v[14:15], v[28:29] op_sel_hi:[1,1,0]
	v_mul_f32_e32 v28, v16, v16
	v_pk_add_f32 v[30:31], v[30:31], v[30:31] op_sel_hi:[0,1]
	v_pk_fma_f32 v[34:35], v[16:17], v[16:17], v[28:29] op_sel_hi:[1,1,0]
	v_pk_mul_f32 v[36:37], v[12:13], v[26:27] op_sel_hi:[1,0]
	v_pk_mul_f32 v[26:27], v[10:11], v[26:27] op_sel_hi:[1,0]
	v_mul_f32_e32 v28, v36, v36
	v_mul_f32_e32 v32, v26, v26
	v_mul_f32_e32 v34, v27, v27
	v_mul_f32_e32 v30, v37, v37
	v_pk_add_f32 v[10:11], v[32:33], v[34:35]
	v_pk_add_f32 v[12:13], v[28:29], v[30:31]
	s_nop 0
	v_pk_add_f32 v[10:11], v[10:11], v[12:13]
	s_nop 0
	v_add_f32_e32 v10, v10, v11
	v_mov_b32_e32 v11, v10
	s_nop 1
	v_permlane16_swap_b32 v10, v11
	s_nop 1
	v_add_f32_e32 v10, v10, v11
	v_mov_b32_e32 v11, v10
	s_nop 1
	v_permlane32_swap_b32 v10, v11
	s_nop 1
	v_add_f32_e32 v10, v10, v11
	v_fmamk_f32 v10, v10, 0x3c800000, v220
	v_rsq_f32_e32 v11, v10
	v_add_u32_e32 v10, s43, v186
	v_cndmask_b32_e64 v28, 1.0, v11, s[40:41]
	v_ashrrev_i32_e32 v11, 31, v10
	v_lshlrev_b64 v[10:11], s42, v[10:11]
	v_lshl_add_u64 v[30:31], v[10:11], 1, v[122:123]
	v_pk_mul_f32 v[10:11], v[22:23], v[28:29] op_sel_hi:[1,0]
	v_pk_mul_f32 v[12:13], v[24:25], v[28:29] op_sel_hi:[1,0]
	v_pk_mul_f32 v[10:11], v[156:157], v[10:11]
	v_pk_mul_f32 v[12:13], v[158:159], v[12:13]
	v_pk_mul_f32 v[18:19], v[18:19], v[28:29] op_sel_hi:[1,0]
	v_pk_mul_f32 v[20:21], v[20:21], v[28:29] op_sel_hi:[1,0]
	v_pk_mul_f32 v[18:19], v[154:155], v[18:19]
	v_pk_mul_f32 v[20:21], v[160:161], v[20:21]
	v_cvt_pk_bf16_f32 v10, v10, v11
	v_cvt_pk_bf16_f32 v11, v12, v13
	v_cvt_pk_bf16_f32 v12, v18, v19
	s_nop 0
	v_cvt_pk_bf16_f32 v13, v20, v21
	global_store_dwordx4 v[30:31], v[10:13], off
	s_nop 1
	v_pk_mul_f32 v[10:11], v[14:15], v[28:29] op_sel_hi:[1,0]
	v_pk_mul_f32 v[12:13], v[16:17], v[28:29] op_sel_hi:[1,0]
	v_pk_mul_f32 v[10:11], v[164:165], v[10:11]
	v_pk_mul_f32 v[12:13], v[166:167], v[12:13]
	v_pk_mul_f32 v[14:15], v[26:27], v[28:29] op_sel_hi:[1,0]
	v_pk_mul_f32 v[16:17], v[36:37], v[28:29] op_sel_hi:[1,0]
	v_pk_mul_f32 v[14:15], v[162:163], v[14:15]
	v_pk_mul_f32 v[16:17], v[168:169], v[16:17]
	v_cvt_pk_bf16_f32 v10, v10, v11
	v_cvt_pk_bf16_f32 v11, v12, v13
	v_cvt_pk_bf16_f32 v12, v14, v15
	s_nop 0
	v_cvt_pk_bf16_f32 v13, v16, v17
	global_store_dwordx4 v[30:31], v[10:13], off offset:64
	s_cbranch_vccnz .LBB0_660
	s_waitcnt vmcnt(0)
	v_add_f32_e32 v10, v6, v7
	v_add_f32_e32 v11, v8, v9
	v_add_f32_e32 v10, v10, v11
	v_add_f32_e32 v11, v2, v3
	v_add_f32_e32 v12, v4, v5
	v_add_f32_e32 v11, v11, v12
	v_add_f32_e32 v10, v11, v10
	ds_bpermute_b32 v11, v1, v10
	s_and_saveexec_b64 s[38:39], s[36:37]
	s_cbranch_execz .LBB0_680
	s_waitcnt lgkmcnt(0)
	v_add_f32_e32 v10, v10, v11
	v_fmamk_f32 v10, v10, 0x3a800000, v220
	v_rsq_f32_e32 v10, v10
	s_lshl_b32 s40, s80, 10
	s_and_b32 s40, s40, 0x400
	v_add_u32_e32 v11, s40, v177
	ds_write_b32 v11, v10
